# attention DMA hooks: second K piece addressed by offset:128 with M0 lowered by 128, column base folded into the scalar tile offset (1 instead of 3 64-bit VALU adds per K part)
# speedup vs baseline: 1.0066x; 1.0038x over previous
.Lattn_A_fast:
	s_lshl_b32 s80, s10, 14
	v_add_u32_e32 v179, s80, v219
	v_add_u32_e32 v126, v179, v149
	ds_read_b128 v[102:105], v126 offset:49152
	ds_read_b128 v[118:121], v126 offset:53248
	ds_read_b128 v[122:125], v126 offset:57344
	ds_read_b128 v[228:231], v126 offset:61440
	s_add_i32 s63, s60, 0x80
	s_lshl_b32 s79, s62, 14
	s_cmp_ge_i32 s61, s48
	s_cselect_b32 s4, 0, 1
	s_waitcnt lgkmcnt(2)
	v_mfma_f32_32x32x16_bf16 v[50:65], v[102:105], v[98:101], v[50:65]
	v_exp_f32_e32 v66, v66
	v_exp_f32_e32 v249, v82
	v_add_u32_e32 v181, v179, v208
	ds_read_b128 v[102:105], v181 offset:49152
	v_mfma_f32_32x32x16_bf16 v[34:49], v[118:121], v[98:101], v[34:49]
	v_add_f32_e32 v254, 0, v66
	v_add_f32_e32 v255, 0, v249
	v_exp_f32_e32 v67, v67
	v_exp_f32_e32 v250, v83
	ds_read_b128 v[232:235], v181 offset:53248
	s_waitcnt lgkmcnt(2)
	v_mfma_f32_32x32x16_bf16 v[18:33], v[122:125], v[98:101], v[18:33]
	v_add_f32_e32 v254, v67, v254
	v_add_f32_e32 v255, v250, v255
	v_exp_f32_e32 v68, v68
	v_exp_f32_e32 v195, v84
	ds_read_b128 v[126:129], v181 offset:57344
	v_mfma_f32_32x32x16_bf16 v[2:17], v[228:231], v[98:101], v[2:17]
	v_add_f32_e32 v254, v68, v254
	v_add_f32_e32 v255, v195, v255
	v_exp_f32_e32 v69, v69
	v_exp_f32_e32 v251, v85
	ds_read_b128 v[118:121], v181 offset:61440
	s_waitcnt lgkmcnt(2)
	v_mfma_f32_32x32x16_bf16 v[50:65], v[102:105], v[106:109], v[50:65]
	v_add_f32_e32 v254, v69, v254
	v_add_f32_e32 v255, v251, v255
	v_exp_f32_e32 v70, v70
	v_exp_f32_e32 v252, v86
	v_add_u32_e32 v181, v179, v209
	ds_read_b128 v[122:125], v181 offset:49152
	v_mfma_f32_32x32x16_bf16 v[34:49], v[232:235], v[106:109], v[34:49]
	s_cbranch_scc1 .LBB0_458
	s_add_i32 s82, s60, 0x100
	s_cmp_le_i32 s61, s39
	s_cselect_b32 s82, s63, s82
	s_lshl_b32 s82, s82, 12
	s_addk_i32 s82, 0x400
	s_add_i32 s78, s79, 0xffffc000
	s_cmp_lg_u32 s62, 0
	s_cselect_b32 s78, s78, 0x8000
	s_add_i32 s78, s7, s78
	s_mov_b32 m0, s78
	v_lshl_add_u64 v[98:99], v[202:203], 0, s[82:83]
	global_load_lds_dwordx4 v[98:99], off
	s_add_i32 m0, s78, 0x1f80
	s_nop 0
	global_load_lds_dwordx4 v[98:99], off offset:128

.LBB0_464:
	s_add_i32 s4, s62, 1
	s_cmp_lg_u32 s62, 2
	s_cselect_b32 s4, s4, 0
	s_add_i32 s5, s10, 1
	s_cmp_lg_u32 s10, 2
	s_cselect_b32 s5, s5, 0
	s_lshl_b32 s62, s5, 14
	v_add_u32_e32 v198, s62, v219
	v_cvt_pk_bf16_f32 v66, v66, v67
	v_cvt_pk_bf16_f32 v67, v68, v69
	v_cvt_pk_bf16_f32 v68, v70, v71
	v_add_u32_e32 v70, v198, v149
	v_cvt_pk_bf16_f32 v69, v82, v83
	v_cvt_pk_bf16_f32 v74, v74, v75
	v_cvt_pk_bf16_f32 v75, v76, v77
	v_cvt_pk_bf16_f32 v76, v78, v79
	v_cvt_pk_bf16_f32 v77, v80, v81
	ds_read_b128 v[78:81], v70 offset:49152
	ds_read_b128 v[82:85], v70 offset:53248
	ds_read_b128 v[86:89], v70 offset:57344
	ds_read_b128 v[228:231], v70 offset:61440
	s_lshl_b32 s10, s4, 14
	s_cmp_gt_i32 s34, s48
	s_waitcnt lgkmcnt(2)
	v_mfma_f32_32x32x16_bf16 v[50:65], v[78:81], v[66:69], v[50:65]
	v_add_u32_e32 v70, v198, v208
	ds_read_b128 v[78:81], v70 offset:49152
	v_mfma_f32_32x32x16_bf16 v[34:49], v[82:85], v[66:69], v[34:49]
	ds_read_b128 v[232:235], v70 offset:53248
	s_waitcnt lgkmcnt(2)
	v_mfma_f32_32x32x16_bf16 v[18:33], v[86:89], v[66:69], v[18:33]
	ds_read_b128 v[86:89], v70 offset:57344
	v_mfma_f32_32x32x16_bf16 v[2:17], v[228:231], v[66:69], v[2:17]
	ds_read_b128 v[82:85], v70 offset:61440
	s_waitcnt lgkmcnt(2)
	v_mfma_f32_32x32x16_bf16 v[50:65], v[78:81], v[74:77], v[50:65]
	v_add_u32_e32 v227, v198, v209
	ds_read_b128 v[78:81], v227 offset:49152
	v_mfma_f32_32x32x16_bf16 v[34:49], v[232:235], v[74:77], v[34:49]
	s_cbranch_scc1 .LBB0_466
	s_cmp_lt_i32 s61, s39
	s_movk_i32 s79, 0xc0
	s_cselect_b32 s79, s79, 0x140
	s_add_i32 s80, s60, s79
	s_lshl_b32 s80, s80, 12
	s_addk_i32 s80, 0x400
	s_add_i32 s60, s10, 0xffffc000
	s_cmp_lg_u32 s4, 0
	s_cselect_b32 s60, s60, 0x8000
	s_add_i32 s60, s7, s60
	s_mov_b32 m0, s60
	v_lshl_add_u64 v[66:67], v[202:203], 0, s[80:81]
	global_load_lds_dwordx4 v[66:67], off
	s_add_i32 m0, s60, 0x1f80
	s_nop 0
	global_load_lds_dwordx4 v[66:67], off offset:128
